# baseline (speedup 1.0000x reference)
; DEVI void gemm_phase(int TID_, int BID_, const u16* __restrict__ A, const u16* __restrict__ Bt, int K, int nN, int epi, u16* Cb, int ldc,
;                      float* Cf, const float* resid, char* shm) {
;     ...
; #pragma unroll
;       for (int m = 0; m < 8; ++m) {
;         const size_t off = (size_t)(crow + wr * 128 + m * 16 + fr) * DM + (ccol + wc * 64 + fq * 8);
;         const float* rp = resid + off;
;         float* cp = Cf + off;
;         float4 r4[4];
; #pragma unroll
;         for (int n = 0; n < 4; ++n) r4[n] = *(const float4*)(rp + (n >> 1) * 32 + (n & 1) * 4);
; #pragma unroll
;         for (int n = 0; n < 4; ++n)
;           *(float4*)(cp + (n >> 1) * 32 + (n & 1) * 4) =
;               make_float4(r4[n].x + acc[m][n][0], r4[n].y + acc[m][n][1], r4[n].z + acc[m][n][2], r4[n].w + acc[m][n][3]);
;         __builtin_amdgcn_sched_barrier(0);
;       }
;     }
.LBB0_662:
	v_lshlrev_b32_e32 v194, 2, v144
	v_lshl_add_u32 v143, v142, 13, v194
	v_lshl_add_u32 v141, v140, 13, v194
	v_lshl_add_u32 v139, v138, 13, v194
	v_lshl_add_u32 v137, v136, 13, v194
	v_lshl_add_u32 v135, v134, 13, v194
	v_lshl_add_u32 v133, v132, 13, v194
	v_lshl_add_u32 v131, v130, 13, v194
	v_lshl_add_u32 v129, v128, 13, v194
	global_load_dwordx4 v[146:149], v143, s[12:13]
	global_load_dwordx4 v[150:153], v143, s[12:13] offset:16
	global_load_dwordx4 v[154:157], v143, s[12:13] offset:128
	global_load_dwordx4 v[158:161], v143, s[12:13] offset:144
	global_load_dwordx4 v[162:165], v141, s[12:13]
	global_load_dwordx4 v[166:169], v141, s[12:13] offset:16
	global_load_dwordx4 v[170:173], v141, s[12:13] offset:128
	global_load_dwordx4 v[174:177], v141, s[12:13] offset:144
	global_load_dwordx4 v[178:181], v139, s[12:13]
	global_load_dwordx4 v[182:185], v139, s[12:13] offset:16
	global_load_dwordx4 v[186:189], v139, s[12:13] offset:128
	global_load_dwordx4 v[190:193], v139, s[12:13] offset:144
	s_waitcnt vmcnt(8)
	v_pk_add_f32 v[146:147], v[124:125], v[146:147]
	v_pk_add_f32 v[148:149], v[126:127], v[148:149]
	v_pk_add_f32 v[150:151], v[120:121], v[150:151]
	v_pk_add_f32 v[152:153], v[122:123], v[152:153]
	v_pk_add_f32 v[154:155], v[116:117], v[154:155]
	v_pk_add_f32 v[156:157], v[118:119], v[156:157]
	v_pk_add_f32 v[158:159], v[112:113], v[158:159]
	v_pk_add_f32 v[160:161], v[114:115], v[160:161]
	global_store_dwordx4 v143, v[146:149], s[14:15]
	global_store_dwordx4 v143, v[150:153], s[14:15] offset:16
	global_store_dwordx4 v143, v[154:157], s[14:15] offset:128
	global_store_dwordx4 v143, v[158:161], s[14:15] offset:144
	global_load_dwordx4 v[124:127], v137, s[12:13]
	global_load_dwordx4 v[120:123], v137, s[12:13] offset:16
	global_load_dwordx4 v[116:119], v137, s[12:13] offset:128
	global_load_dwordx4 v[112:115], v137, s[12:13] offset:144
	s_waitcnt vmcnt(12)
	v_pk_add_f32 v[162:163], v[108:109], v[162:163]
	v_pk_add_f32 v[164:165], v[110:111], v[164:165]
	v_pk_add_f32 v[166:167], v[104:105], v[166:167]
	v_pk_add_f32 v[168:169], v[106:107], v[168:169]
	v_pk_add_f32 v[170:171], v[100:101], v[170:171]
	v_pk_add_f32 v[172:173], v[102:103], v[172:173]
	v_pk_add_f32 v[174:175], v[96:97], v[174:175]
	v_pk_add_f32 v[176:177], v[98:99], v[176:177]
	global_store_dwordx4 v141, v[162:165], s[14:15]
	global_store_dwordx4 v141, v[166:169], s[14:15] offset:16
	global_store_dwordx4 v141, v[170:173], s[14:15] offset:128
	global_store_dwordx4 v141, v[174:177], s[14:15] offset:144
	global_load_dwordx4 v[108:111], v135, s[12:13]
	global_load_dwordx4 v[104:107], v135, s[12:13] offset:16
	global_load_dwordx4 v[100:103], v135, s[12:13] offset:128
	global_load_dwordx4 v[96:99], v135, s[12:13] offset:144
	s_waitcnt vmcnt(16)
	v_pk_add_f32 v[178:179], v[92:93], v[178:179]
	v_pk_add_f32 v[180:181], v[94:95], v[180:181]
	v_pk_add_f32 v[182:183], v[88:89], v[182:183]
	v_pk_add_f32 v[184:185], v[90:91], v[184:185]
	v_pk_add_f32 v[186:187], v[84:85], v[186:187]
	v_pk_add_f32 v[188:189], v[86:87], v[188:189]
	v_pk_add_f32 v[190:191], v[80:81], v[190:191]
	v_pk_add_f32 v[192:193], v[82:83], v[192:193]
	global_store_dwordx4 v139, v[178:181], s[14:15]
	global_store_dwordx4 v139, v[182:185], s[14:15] offset:16
	global_store_dwordx4 v139, v[186:189], s[14:15] offset:128
	global_store_dwordx4 v139, v[190:193], s[14:15] offset:144
	global_load_dwordx4 v[92:95], v133, s[12:13]
	global_load_dwordx4 v[88:91], v133, s[12:13] offset:16
	global_load_dwordx4 v[84:87], v133, s[12:13] offset:128
	global_load_dwordx4 v[80:83], v133, s[12:13] offset:144
	s_waitcnt vmcnt(16)
	v_pk_add_f32 v[124:125], v[76:77], v[124:125]
	v_pk_add_f32 v[126:127], v[78:79], v[126:127]
	v_pk_add_f32 v[120:121], v[72:73], v[120:121]
	v_pk_add_f32 v[122:123], v[74:75], v[122:123]
	v_pk_add_f32 v[116:117], v[68:69], v[116:117]
	v_pk_add_f32 v[118:119], v[70:71], v[118:119]
	v_pk_add_f32 v[112:113], v[56:57], v[112:113]
	v_pk_add_f32 v[114:115], v[58:59], v[114:115]
	global_store_dwordx4 v137, v[124:127], s[14:15]
	global_store_dwordx4 v137, v[120:123], s[14:15] offset:16
	global_store_dwordx4 v137, v[116:119], s[14:15] offset:128
	global_store_dwordx4 v137, v[112:115], s[14:15] offset:144
	global_load_dwordx4 v[76:79], v131, s[12:13]
	global_load_dwordx4 v[72:75], v131, s[12:13] offset:16
	global_load_dwordx4 v[68:71], v131, s[12:13] offset:128
	global_load_dwordx4 v[56:59], v131, s[12:13] offset:144
	s_waitcnt vmcnt(16)
	v_pk_add_f32 v[108:109], v[28:29], v[108:109]
	v_pk_add_f32 v[110:111], v[30:31], v[110:111]
	v_pk_add_f32 v[104:105], v[24:25], v[104:105]
	v_pk_add_f32 v[106:107], v[26:27], v[106:107]
	v_pk_add_f32 v[100:101], v[20:21], v[100:101]
	v_pk_add_f32 v[102:103], v[22:23], v[102:103]
	v_pk_add_f32 v[96:97], v[16:17], v[96:97]
	v_pk_add_f32 v[98:99], v[18:19], v[98:99]
	global_store_dwordx4 v135, v[108:111], s[14:15]
	global_store_dwordx4 v135, v[104:107], s[14:15] offset:16
	global_store_dwordx4 v135, v[100:103], s[14:15] offset:128
	global_store_dwordx4 v135, v[96:99], s[14:15] offset:144
	global_load_dwordx4 v[28:31], v129, s[12:13]
	global_load_dwordx4 v[24:27], v129, s[12:13] offset:16
	global_load_dwordx4 v[20:23], v129, s[12:13] offset:128
	global_load_dwordx4 v[16:19], v129, s[12:13] offset:144
	s_waitcnt vmcnt(16)
	v_pk_add_f32 v[92:93], v[12:13], v[92:93]
	v_pk_add_f32 v[94:95], v[14:15], v[94:95]
	v_pk_add_f32 v[88:89], v[8:9], v[88:89]
	v_pk_add_f32 v[90:91], v[10:11], v[90:91]
	v_pk_add_f32 v[84:85], v[4:5], v[84:85]
	v_pk_add_f32 v[86:87], v[6:7], v[86:87]
	v_pk_add_f32 v[80:81], v[0:1], v[80:81]
	v_pk_add_f32 v[82:83], v[2:3], v[82:83]
	global_store_dwordx4 v133, v[92:95], s[14:15]
	global_store_dwordx4 v133, v[88:91], s[14:15] offset:16
	global_store_dwordx4 v133, v[84:87], s[14:15] offset:128
	global_store_dwordx4 v133, v[80:83], s[14:15] offset:144
	s_waitcnt vmcnt(12)
	v_pk_add_f32 v[76:77], v[52:53], v[76:77]
	v_pk_add_f32 v[78:79], v[54:55], v[78:79]
	v_pk_add_f32 v[72:73], v[64:65], v[72:73]
	v_pk_add_f32 v[74:75], v[66:67], v[74:75]
	v_pk_add_f32 v[68:69], v[48:49], v[68:69]
	v_pk_add_f32 v[70:71], v[50:51], v[70:71]
	v_pk_add_f32 v[56:57], v[60:61], v[56:57]
	v_pk_add_f32 v[58:59], v[62:63], v[58:59]
	global_store_dwordx4 v131, v[76:79], s[14:15]
	global_store_dwordx4 v131, v[72:75], s[14:15] offset:16
	global_store_dwordx4 v131, v[68:71], s[14:15] offset:128
	global_store_dwordx4 v131, v[56:59], s[14:15] offset:144
	s_waitcnt vmcnt(8)
	v_pk_add_f32 v[28:29], v[36:37], v[28:29]
	v_pk_add_f32 v[30:31], v[38:39], v[30:31]
	v_pk_add_f32 v[24:25], v[44:45], v[24:25]
	v_pk_add_f32 v[26:27], v[46:47], v[26:27]
	v_pk_add_f32 v[20:21], v[32:33], v[20:21]
	v_pk_add_f32 v[22:23], v[34:35], v[22:23]
	v_pk_add_f32 v[16:17], v[40:41], v[16:17]
	v_pk_add_f32 v[18:19], v[42:43], v[18:19]
	global_store_dwordx4 v129, v[28:31], s[14:15]
	global_store_dwordx4 v129, v[24:27], s[14:15] offset:16
	global_store_dwordx4 v129, v[20:23], s[14:15] offset:128
	global_store_dwordx4 v129, v[16:19], s[14:15] offset:144
	s_cbranch_execnz .LBB0_653
